# out-projection GEMM loop: LDS-DMA double-buffered swizzled stages instead of register-staged ds_write double buffer
# speedup vs baseline: 1.1136x; 1.0128x over previous
.LBB0_56:
	s_lshl_b32 s4, s6, 4
	s_and_b32 s38, s4, 0x7fffff80
	s_lshl_b32 s4, s6, 7
	s_mov_b32 s39, s97
	v_mov_b32_e32 v46, v133
	s_and_b32 s7, s4, 0x380
	s_lshl_b64 s[4:5], s[38:39], 11
	s_add_u32 s46, s88, s4
	v_lshlrev_b32_e32 v0, 3, v46
	v_and_b32_e32 v131, 56, v0
	v_lshlrev_b32_e32 v0, 7, v46
	s_addc_u32 s47, s89, s5
	s_lshl_b32 s4, s7, 11
	v_and_b32_e32 v135, 0xfffffc00, v0
	s_add_u32 s48, s18, s4
	v_or_b32_e32 v0, v131, v135
	v_add_u32_e32 v152, 0x8000, v135
	s_addc_u32 s49, s19, 0
	v_lshlrev_b64 v[2:3], 1, v[0:1]
	v_or_b32_e32 v0, v152, v131
	v_add_u32_e32 v156, 0x10000, v135
	v_lshl_add_u64 v[158:159], s[46:47], 0, v[2:3]
	v_lshl_add_u64 v[160:161], s[48:49], 0, v[2:3]
	v_lshlrev_b64 v[2:3], 1, v[0:1]
	v_or_b32_e32 v0, v156, v131
	v_add_u32_e32 v162, 0x18000, v135
	v_lshl_add_u64 v[34:35], s[46:47], 0, v[2:3]
	v_lshl_add_u64 v[36:37], s[48:49], 0, v[2:3]
	v_lshlrev_b64 v[2:3], 1, v[0:1]
	v_or_b32_e32 v0, v162, v131
	v_lshl_add_u64 v[38:39], s[46:47], 0, v[2:3]
	v_lshl_add_u64 v[40:41], s[48:49], 0, v[2:3]
	v_lshlrev_b64 v[2:3], 1, v[0:1]
	v_lshl_add_u64 v[42:43], s[46:47], 0, v[2:3]
	v_lshl_add_u64 v[44:45], s[48:49], 0, v[2:3]
	v_and_b32_e32 v78, 63, v133
	v_lshrrev_b32_e32 v79, 6, v133
	v_lshlrev_b32_e32 v80, 12, v79
	v_lshrrev_b32_e32 v81, 3, v78
	v_readfirstlane_b32 s4, v80
	v_lshl_add_u32 v81, v79, 5, v81
	v_lshlrev_b32_e32 v81, 11, v81
	v_and_b32_e32 v82, 7, v78
	v_lshrrev_b32_e32 v83, 4, v78
	v_xor_b32_e32 v82, v82, v83
	v_xor_b32_e32 v83, 4, v82
	v_lshl_add_u32 v66, v82, 4, v81
	v_lshl_add_u32 v67, v83, 4, v81
	v_add_u32_e32 v67, 0x4000, v67
	v_add_u32_e32 v68, 0x8000, v66
	v_add_u32_e32 v69, 0x8000, v67
	v_and_b32_e32 v80, 31, v78
	v_lshrrev_b32_e32 v81, 5, v78
	v_bfe_u32 v82, v78, 1, 3
	v_xor_b32_e32 v81, v81, v82
	v_lshrrev_b32_e32 v82, 1, v79
	v_and_b32_e32 v83, 1, v79
	v_lshl_add_u32 v82, v82, 6, v80
	v_lshl_add_u32 v83, v83, 6, v80
	v_lshlrev_b32_e32 v82, 7, v82
	v_lshlrev_b32_e32 v83, 7, v83
	v_add_u32_e32 v83, 0x4000, v83
	v_lshl_add_u32 v70, v81, 4, v82
	v_lshl_add_u32 v74, v81, 4, v83
	v_xor_b32_e32 v84, 2, v81
	v_lshl_add_u32 v71, v84, 4, v82
	v_lshl_add_u32 v75, v84, 4, v83
	v_xor_b32_e32 v84, 4, v81
	v_lshl_add_u32 v72, v84, 4, v82
	v_lshl_add_u32 v76, v84, 4, v83
	v_xor_b32_e32 v84, 6, v81
	v_lshl_add_u32 v73, v84, 4, v82
	v_lshl_add_u32 v77, v84, 4, v83
	s_waitcnt lgkmcnt(0)
	s_barrier
	s_add_u32 m0, s4, 0x0
	s_nop 0
	global_load_lds_dwordx4 v66, s[46:47]
	s_add_u32 m0, s4, 0x400
	s_nop 0
	global_load_lds_dwordx4 v67, s[46:47]
	s_add_u32 m0, s4, 0x800
	s_nop 0
	global_load_lds_dwordx4 v68, s[46:47]
	s_add_u32 m0, s4, 0xc00
	s_nop 0
	global_load_lds_dwordx4 v69, s[46:47]
	s_add_u32 m0, s4, 0x4000
	s_nop 0
	global_load_lds_dwordx4 v66, s[48:49]
	s_add_u32 m0, s4, 0x4400
	s_nop 0
	global_load_lds_dwordx4 v67, s[48:49]
	s_add_u32 m0, s4, 0x4800
	s_nop 0
	global_load_lds_dwordx4 v68, s[48:49]
	s_add_u32 m0, s4, 0x4c00
	s_nop 0
	global_load_lds_dwordx4 v69, s[48:49]
	v_add_u32_e32 v66, 0x80, v66
	v_add_u32_e32 v67, 0x80, v67
	v_add_u32_e32 v68, 0x80, v68
	v_add_u32_e32 v69, 0x80, v69
	v_mov_b32_e32 v2, 0
	v_mov_b32_e32 v3, 0
	v_mov_b32_e32 v4, 0
	v_mov_b32_e32 v5, 0
	v_mov_b32_e32 v6, 0
	v_mov_b32_e32 v7, 0
	v_mov_b32_e32 v8, 0
	v_mov_b32_e32 v9, 0
	v_mov_b32_e32 v10, 0
	v_mov_b32_e32 v11, 0
	v_mov_b32_e32 v12, 0
	v_mov_b32_e32 v13, 0
	v_mov_b32_e32 v14, 0
	v_mov_b32_e32 v15, 0
	v_mov_b32_e32 v16, 0
	v_mov_b32_e32 v17, 0
	v_mov_b32_e32 v18, 0
	v_mov_b32_e32 v19, 0
	v_mov_b32_e32 v20, 0
	v_mov_b32_e32 v21, 0
	v_mov_b32_e32 v22, 0
	v_mov_b32_e32 v23, 0
	v_mov_b32_e32 v24, 0
	v_mov_b32_e32 v25, 0
	v_mov_b32_e32 v26, 0
	v_mov_b32_e32 v27, 0
	v_mov_b32_e32 v28, 0
	v_mov_b32_e32 v29, 0
	v_mov_b32_e32 v30, 0
	v_mov_b32_e32 v31, 0
	v_mov_b32_e32 v32, 0
	v_mov_b32_e32 v33, 0
	v_mov_b32_e32 v34, 0
	v_mov_b32_e32 v35, 0
	v_mov_b32_e32 v36, 0
	v_mov_b32_e32 v37, 0
	v_mov_b32_e32 v38, 0
	v_mov_b32_e32 v39, 0
	v_mov_b32_e32 v40, 0
	v_mov_b32_e32 v41, 0
	v_mov_b32_e32 v42, 0
	v_mov_b32_e32 v43, 0
	v_mov_b32_e32 v44, 0
	v_mov_b32_e32 v45, 0
	v_mov_b32_e32 v46, 0
	v_mov_b32_e32 v47, 0
	v_mov_b32_e32 v48, 0
	v_mov_b32_e32 v49, 0
	v_mov_b32_e32 v50, 0
	v_mov_b32_e32 v51, 0
	v_mov_b32_e32 v52, 0
	v_mov_b32_e32 v53, 0
	v_mov_b32_e32 v54, 0
	v_mov_b32_e32 v55, 0
	v_mov_b32_e32 v56, 0
	v_mov_b32_e32 v57, 0
	v_mov_b32_e32 v58, 0
	v_mov_b32_e32 v59, 0
	v_mov_b32_e32 v60, 0
	v_mov_b32_e32 v61, 0
	v_mov_b32_e32 v62, 0
	v_mov_b32_e32 v63, 0
	v_mov_b32_e32 v64, 0
	v_mov_b32_e32 v65, 0
	s_mov_b32 s8, 0
	s_waitcnt vmcnt(0)
.Lout_loop:
	s_barrier
	s_add_u32 m0, s4, 0x8000
	s_nop 0
	global_load_lds_dwordx4 v66, s[46:47]
	s_add_u32 m0, s4, 0x8400
	s_nop 0
	global_load_lds_dwordx4 v67, s[46:47]
	s_add_u32 m0, s4, 0x8800
	s_nop 0
	global_load_lds_dwordx4 v68, s[46:47]
	s_add_u32 m0, s4, 0x8c00
	s_nop 0
	global_load_lds_dwordx4 v69, s[46:47]
	s_add_u32 m0, s4, 0xc000
	s_nop 0
	global_load_lds_dwordx4 v66, s[48:49]
	s_add_u32 m0, s4, 0xc400
	s_nop 0
	global_load_lds_dwordx4 v67, s[48:49]
	s_add_u32 m0, s4, 0xc800
	s_nop 0
	global_load_lds_dwordx4 v68, s[48:49]
	s_add_u32 m0, s4, 0xcc00
	s_nop 0
	global_load_lds_dwordx4 v69, s[48:49]
	v_add_u32_e32 v66, 0x80, v66
	v_add_u32_e32 v67, 0x80, v67
	v_add_u32_e32 v68, 0x80, v68
	v_add_u32_e32 v69, 0x80, v69
	ds_read_b128 v[90:93], v70
	ds_read_b128 v[98:101], v74
	ds_read_b128 v[102:105], v74 offset:4096
	ds_read_b128 v[94:97], v70 offset:4096
	s_waitcnt lgkmcnt(2)
	v_mfma_f32_32x32x16_bf16 v[50:65], v[90:93], v[98:101], v[50:65]
	s_waitcnt lgkmcnt(1)
	v_mfma_f32_32x32x16_bf16 v[34:49], v[90:93], v[102:105], v[34:49]
	ds_read_b128 v[90:93], v71
	s_waitcnt lgkmcnt(1)
	v_mfma_f32_32x32x16_bf16 v[18:33], v[94:97], v[98:101], v[18:33]
	ds_read_b128 v[98:101], v75
	v_mfma_f32_32x32x16_bf16 v[2:17], v[94:97], v[102:105], v[2:17]
	ds_read_b128 v[102:105], v75 offset:4096
	ds_read_b128 v[94:97], v71 offset:4096
	s_waitcnt lgkmcnt(2)
	v_mfma_f32_32x32x16_bf16 v[50:65], v[90:93], v[98:101], v[50:65]
	s_waitcnt lgkmcnt(1)
	v_mfma_f32_32x32x16_bf16 v[34:49], v[90:93], v[102:105], v[34:49]
	ds_read_b128 v[90:93], v72
	s_waitcnt lgkmcnt(1)
	v_mfma_f32_32x32x16_bf16 v[18:33], v[94:97], v[98:101], v[18:33]
	ds_read_b128 v[98:101], v76
	v_mfma_f32_32x32x16_bf16 v[2:17], v[94:97], v[102:105], v[2:17]
	ds_read_b128 v[102:105], v76 offset:4096
	ds_read_b128 v[94:97], v72 offset:4096
	s_waitcnt lgkmcnt(2)
	v_mfma_f32_32x32x16_bf16 v[50:65], v[90:93], v[98:101], v[50:65]
	s_waitcnt lgkmcnt(1)
	v_mfma_f32_32x32x16_bf16 v[34:49], v[90:93], v[102:105], v[34:49]
	ds_read_b128 v[90:93], v73
	s_waitcnt lgkmcnt(1)
	v_mfma_f32_32x32x16_bf16 v[18:33], v[94:97], v[98:101], v[18:33]
	ds_read_b128 v[98:101], v77
	v_mfma_f32_32x32x16_bf16 v[2:17], v[94:97], v[102:105], v[2:17]
	ds_read_b128 v[102:105], v77 offset:4096
	ds_read_b128 v[94:97], v73 offset:4096
	s_waitcnt lgkmcnt(2)
	v_mfma_f32_32x32x16_bf16 v[50:65], v[90:93], v[98:101], v[50:65]
	s_waitcnt lgkmcnt(1)
	v_mfma_f32_32x32x16_bf16 v[34:49], v[90:93], v[102:105], v[34:49]
	s_waitcnt lgkmcnt(0)
	v_mfma_f32_32x32x16_bf16 v[18:33], v[94:97], v[98:101], v[18:33]
	v_mfma_f32_32x32x16_bf16 v[2:17], v[94:97], v[102:105], v[2:17]
	s_waitcnt vmcnt(0)
	s_barrier
	s_cmp_eq_u32 s8, 7
	s_cbranch_scc1 .Lout_skip
	s_add_u32 m0, s4, 0x0
	s_nop 0
	global_load_lds_dwordx4 v66, s[46:47]
	s_add_u32 m0, s4, 0x400
	s_nop 0
	global_load_lds_dwordx4 v67, s[46:47]
	s_add_u32 m0, s4, 0x800
	s_nop 0
	global_load_lds_dwordx4 v68, s[46:47]
	s_add_u32 m0, s4, 0xc00
	s_nop 0
	global_load_lds_dwordx4 v69, s[46:47]
	s_add_u32 m0, s4, 0x4000
	s_nop 0
	global_load_lds_dwordx4 v66, s[48:49]
	s_add_u32 m0, s4, 0x4400
	s_nop 0
	global_load_lds_dwordx4 v67, s[48:49]
	s_add_u32 m0, s4, 0x4800
	s_nop 0
	global_load_lds_dwordx4 v68, s[48:49]
	s_add_u32 m0, s4, 0x4c00
	s_nop 0
	global_load_lds_dwordx4 v69, s[48:49]
	v_add_u32_e32 v66, 0x80, v66
	v_add_u32_e32 v67, 0x80, v67
	v_add_u32_e32 v68, 0x80, v68
	v_add_u32_e32 v69, 0x80, v69
.Lout_skip:
	ds_read_b128 v[90:93], v70 offset:32768
	ds_read_b128 v[98:101], v74 offset:32768
	ds_read_b128 v[102:105], v74 offset:36864
	ds_read_b128 v[94:97], v70 offset:36864
	s_waitcnt lgkmcnt(2)
	v_mfma_f32_32x32x16_bf16 v[50:65], v[90:93], v[98:101], v[50:65]
	s_waitcnt lgkmcnt(1)
	v_mfma_f32_32x32x16_bf16 v[34:49], v[90:93], v[102:105], v[34:49]
	ds_read_b128 v[90:93], v71 offset:32768
	s_waitcnt lgkmcnt(1)
	v_mfma_f32_32x32x16_bf16 v[18:33], v[94:97], v[98:101], v[18:33]
	ds_read_b128 v[98:101], v75 offset:32768
	v_mfma_f32_32x32x16_bf16 v[2:17], v[94:97], v[102:105], v[2:17]
	ds_read_b128 v[102:105], v75 offset:36864
	ds_read_b128 v[94:97], v71 offset:36864
	s_waitcnt lgkmcnt(2)
	v_mfma_f32_32x32x16_bf16 v[50:65], v[90:93], v[98:101], v[50:65]
	s_waitcnt lgkmcnt(1)
	v_mfma_f32_32x32x16_bf16 v[34:49], v[90:93], v[102:105], v[34:49]
	ds_read_b128 v[90:93], v72 offset:32768
	s_waitcnt lgkmcnt(1)
	v_mfma_f32_32x32x16_bf16 v[18:33], v[94:97], v[98:101], v[18:33]
	ds_read_b128 v[98:101], v76 offset:32768
	v_mfma_f32_32x32x16_bf16 v[2:17], v[94:97], v[102:105], v[2:17]
	ds_read_b128 v[102:105], v76 offset:36864
	ds_read_b128 v[94:97], v72 offset:36864
	s_waitcnt lgkmcnt(2)
	v_mfma_f32_32x32x16_bf16 v[50:65], v[90:93], v[98:101], v[50:65]
	s_waitcnt lgkmcnt(1)
	v_mfma_f32_32x32x16_bf16 v[34:49], v[90:93], v[102:105], v[34:49]
	ds_read_b128 v[90:93], v73 offset:32768
	s_waitcnt lgkmcnt(1)
	v_mfma_f32_32x32x16_bf16 v[18:33], v[94:97], v[98:101], v[18:33]
	ds_read_b128 v[98:101], v77 offset:32768
	v_mfma_f32_32x32x16_bf16 v[2:17], v[94:97], v[102:105], v[2:17]
	ds_read_b128 v[102:105], v77 offset:36864
	ds_read_b128 v[94:97], v73 offset:36864
	s_waitcnt lgkmcnt(2)
	v_mfma_f32_32x32x16_bf16 v[50:65], v[90:93], v[98:101], v[50:65]
	s_waitcnt lgkmcnt(1)
	v_mfma_f32_32x32x16_bf16 v[34:49], v[90:93], v[102:105], v[34:49]
	s_waitcnt lgkmcnt(0)
	v_mfma_f32_32x32x16_bf16 v[18:33], v[94:97], v[98:101], v[18:33]
	v_mfma_f32_32x32x16_bf16 v[2:17], v[94:97], v[102:105], v[2:17]
	s_waitcnt vmcnt(0)
	s_add_i32 s8, s8, 1
	s_cmp_lg_u32 s8, 8
	s_cbranch_scc1 .Lout_loop
	s_nop 15
